# gate/up K-loop: fragment reads reordered k0-first with counted lgkmcnt so the first 8 MFMAs of a phase start after half the LDS reads
# baseline (speedup 1.0000x reference)
; #define PG8_STAGE(bufoff, gbase, voff) do { _Pragma("unroll") for (int _i = 0; _i < 2; ++_i) \
;         __builtin_amdgcn_global_load_lds((const unsigned*)((const char*)(gbase) + (voff)[_i]), (LAS unsigned*)(lds + (bufoff) + ldsw + _i * 8192), 16, 0, 0); } while (0)
; #define PG8_LDA(dst, b, h) do { _Pragma("unroll") for (int m = 0; m < 4; ++m) _Pragma("unroll") for (int k = 0; k < 2; ++k) dst[m][k] = *(const LAS bf16x8*)(lds + PG8_SA(b, h) + aoff + m * 2048 + k * 1024); } while (0)
; #define PG8_LDB(dst, b, h) do { _Pragma("unroll") for (int n = 0; n < 2; ++n) _Pragma("unroll") for (int k = 0; k < 2; ++k) dst[n][k] = *(const LAS bf16x8*)(lds + PG8_SB(b, h) + boff + n * 2048 + k * 1024); } while (0)
; #define PG8_MMA(ai, bj, At, Bt) do { __builtin_amdgcn_s_setprio(1); _Pragma("unroll") for (int m = 0; m < 4; ++m) _Pragma("unroll") for (int n = 0; n < 2; ++n) _Pragma("unroll") for (int k = 0; k < 2; ++k) \
;         acc[ai][bj][m][n] = __builtin_amdgcn_mfma_f32_16x16x32_bf16(Bt[n][k], At[m][k], acc[ai][bj][m][n], 0, 0, 0); __builtin_amdgcn_s_setprio(0); } while (0)
; #define PG8_WAIT_V(n) asm volatile("s_waitcnt vmcnt(" #n ")" ::: "memory")
; #define PG8_WAIT_L(n) asm volatile("s_waitcnt lgkmcnt(" #n ")" ::: "memory")
; template <class Epi, class Sched>
; __device__ __forceinline__ void gemm_phase(LAS unsigned char* lds, const Gemm g, const Sched& S, const Epi& E, const Ids I) {
;     ...
;             PG8_LDB(B0, 0, 0); PG8_SCHED; PG8_LDA(At, 0, 0); PG8_STAGE(PG8_SA(1, 1), a1 + hstep, voffA);
;             PG8_WAIT_L(8); PG8_BAR; PG8_WAIT_L(0); PG8_MMA(0, 0, At, B0); PG8_BAR; PG8_SCHED;
;             PG8_LDB(B1, 0, 1); PG8_STAGE(PG8_SB(0, 0), b2, voffB);
;             PG8_BAR; PG8_WAIT_L(0); PG8_MMA(0, 1, At, B1); PG8_BAR;
;             PG8_LDA(At, 0, 1); PG8_STAGE(PG8_SA(0, 0), a2, voffA);
;             PG8_BAR; PG8_WAIT_L(0); PG8_MMA(1, 0, At, B0); PG8_BAR; PG8_SCHED;
;             PG8_STAGE(PG8_SB(0, 1), b2 + hstep, voffB);
;             PG8_WAIT_V(6); PG8_BAR; PG8_MMA(1, 1, At, B1); PG8_BAR;
;             PG8_LDB(B0, 1, 0); PG8_SCHED; PG8_LDA(At, 1, 0); PG8_STAGE(PG8_SA(0, 1), a2 + hstep, voffA);
;             PG8_WAIT_L(8); PG8_BAR; PG8_WAIT_L(0); PG8_MMA(0, 0, At, B0); PG8_BAR; PG8_SCHED;
;             PG8_LDB(B1, 1, 1); PG8_STAGE(PG8_SB(1, 0), b3, voffB);
;             PG8_BAR; PG8_WAIT_L(0); PG8_MMA(0, 1, At, B1); PG8_BAR;
.LBB0_408:
	s_add_u32 s20, s18, 0xfffc0080
	s_addc_u32 s21, s19, -1
	s_add_i32 s39, 0, 0x10000
	v_add_u32_e32 v228, s39, v137
	ds_read_b128 v[140:143], v228
	ds_read_b128 v[156:159], v228 offset:2048
	ds_read_b128 v[164:167], v139
	ds_read_b128 v[188:191], v139 offset:2048
	s_cmp_eq_u32 s38, 12
	s_cselect_b32 s23, s3, s21
	s_cselect_b32 s22, s9, s20
	s_cselect_b32 s21, s7, s37
	s_cselect_b32 s20, s35, s36
	v_lshl_add_u64 v[134:135], s[18:19], 0, v[130:131]
	s_add_i32 m0, s17, 0xc000
	ds_read_b128 v[196:199], v139 offset:4096
	ds_read_b128 v[204:207], v139 offset:6144
	ds_read_b128 v[152:155], v228 offset:1024
	ds_read_b128 v[160:163], v228 offset:3072
	ds_read_b128 v[168:171], v139 offset:1024
	ds_read_b128 v[192:195], v139 offset:3072
	ds_read_b128 v[200:203], v139 offset:5120
	ds_read_b128 v[208:211], v139 offset:7168
	global_load_lds_dwordx4 v[134:135], off
	v_lshl_add_u64 v[134:135], s[18:19], 0, v[132:133]
	s_add_i32 m0, s17, 0xe000
	s_nop 0
	global_load_lds_dwordx4 v[134:135], off
	s_waitcnt lgkmcnt(8)
	s_barrier
	s_waitcnt lgkmcnt(6)
	s_setprio 1
	s_waitcnt lgkmcnt(6)
	v_mfma_f32_16x16x32_bf16 v[124:127], v[140:143], v[164:167], v[124:127]
	v_mfma_f32_16x16x32_bf16 v[116:119], v[156:159], v[164:167], v[116:119]
	v_mfma_f32_16x16x32_bf16 v[108:111], v[140:143], v[188:191], v[108:111]
	v_mfma_f32_16x16x32_bf16 v[100:103], v[156:159], v[188:191], v[100:103]
	v_mfma_f32_16x16x32_bf16 v[92:95], v[140:143], v[196:199], v[92:95]
	v_mfma_f32_16x16x32_bf16 v[84:87], v[156:159], v[196:199], v[84:87]
	v_mfma_f32_16x16x32_bf16 v[76:79], v[140:143], v[204:207], v[76:79]
	v_mfma_f32_16x16x32_bf16 v[68:71], v[156:159], v[204:207], v[68:71]
	s_waitcnt lgkmcnt(0)
	v_mfma_f32_16x16x32_bf16 v[124:127], v[152:155], v[168:171], v[124:127]
	v_mfma_f32_16x16x32_bf16 v[116:119], v[160:163], v[168:171], v[116:119]
	v_mfma_f32_16x16x32_bf16 v[108:111], v[152:155], v[192:195], v[108:111]
	v_mfma_f32_16x16x32_bf16 v[100:103], v[160:163], v[192:195], v[100:103]
	v_mfma_f32_16x16x32_bf16 v[92:95], v[152:155], v[200:203], v[92:95]
	v_mfma_f32_16x16x32_bf16 v[84:87], v[160:163], v[200:203], v[84:87]
	v_mfma_f32_16x16x32_bf16 v[76:79], v[152:155], v[208:211], v[76:79]
	v_mfma_f32_16x16x32_bf16 v[68:71], v[160:163], v[208:211], v[68:71]
	s_setprio 0
	s_barrier
	s_add_i32 s42, 0, 0x14000
	v_add_u32_e32 v134, s42, v137
	s_add_i32 s39, s39, s25
	ds_read_b128 v[212:215], v134
	ds_read_b128 v[220:223], v134 offset:2048
	ds_read_b128 v[216:219], v134 offset:1024
	ds_read_b128 v[224:227], v134 offset:3072
	v_lshl_add_u64 v[134:135], s[20:21], 0, v[144:145]
	s_mov_b32 m0, s39
	v_lshl_add_u64 v[172:173], s[20:21], 0, v[128:129]
	global_load_lds_dwordx4 v[134:135], off
	s_add_i32 m0, s39, 0x2000
	s_nop 0
	global_load_lds_dwordx4 v[172:173], off
	s_barrier
	s_waitcnt lgkmcnt(2)
	s_setprio 1
	s_waitcnt lgkmcnt(2)
	v_mfma_f32_16x16x32_bf16 v[120:123], v[212:215], v[164:167], v[120:123]
	v_mfma_f32_16x16x32_bf16 v[112:115], v[220:223], v[164:167], v[112:115]
	v_mfma_f32_16x16x32_bf16 v[104:107], v[212:215], v[188:191], v[104:107]
	v_mfma_f32_16x16x32_bf16 v[96:99], v[220:223], v[188:191], v[96:99]
	v_mfma_f32_16x16x32_bf16 v[88:91], v[212:215], v[196:199], v[88:91]
	v_mfma_f32_16x16x32_bf16 v[80:83], v[220:223], v[196:199], v[80:83]
	v_mfma_f32_16x16x32_bf16 v[72:75], v[212:215], v[204:207], v[72:75]
	v_mfma_f32_16x16x32_bf16 v[64:67], v[220:223], v[204:207], v[64:67]
	s_waitcnt lgkmcnt(0)
	v_mfma_f32_16x16x32_bf16 v[120:123], v[216:219], v[168:171], v[120:123]
	v_mfma_f32_16x16x32_bf16 v[112:115], v[224:227], v[168:171], v[112:115]
	v_mfma_f32_16x16x32_bf16 v[104:107], v[216:219], v[192:195], v[104:107]
	v_mfma_f32_16x16x32_bf16 v[96:99], v[224:227], v[192:195], v[96:99]
	v_mfma_f32_16x16x32_bf16 v[88:91], v[216:219], v[200:203], v[88:91]
	v_mfma_f32_16x16x32_bf16 v[80:83], v[224:227], v[200:203], v[80:83]
	v_mfma_f32_16x16x32_bf16 v[72:75], v[216:219], v[208:211], v[72:75]
	v_mfma_f32_16x16x32_bf16 v[64:67], v[224:227], v[208:211], v[64:67]
	s_setprio 0
	s_mov_b32 m0, s17
	v_lshl_add_u64 v[176:177], s[22:23], 0, v[144:145]
	s_barrier
	ds_read_b128 v[164:167], v139 offset:16384
	ds_read_b128 v[188:191], v139 offset:18432
	ds_read_b128 v[196:199], v139 offset:20480
	ds_read_b128 v[204:207], v139 offset:22528
	ds_read_b128 v[168:171], v139 offset:17408
	ds_read_b128 v[192:195], v139 offset:19456
	ds_read_b128 v[200:203], v139 offset:21504
	ds_read_b128 v[208:211], v139 offset:23552
	global_load_lds_dwordx4 v[176:177], off
	v_lshl_add_u64 v[178:179], s[22:23], 0, v[128:129]
	s_mov_b32 m0, s28
	s_nop 0
	global_load_lds_dwordx4 v[178:179], off
	s_barrier
	s_waitcnt lgkmcnt(4)
	s_setprio 1
	s_waitcnt lgkmcnt(4)
	v_mfma_f32_16x16x32_bf16 v[60:63], v[140:143], v[164:167], v[60:63]
	v_mfma_f32_16x16x32_bf16 v[52:55], v[156:159], v[164:167], v[52:55]
	v_mfma_f32_16x16x32_bf16 v[44:47], v[140:143], v[188:191], v[44:47]
	v_mfma_f32_16x16x32_bf16 v[36:39], v[156:159], v[188:191], v[36:39]
	v_mfma_f32_16x16x32_bf16 v[28:31], v[140:143], v[196:199], v[28:31]
	v_mfma_f32_16x16x32_bf16 v[20:23], v[156:159], v[196:199], v[20:23]
	v_mfma_f32_16x16x32_bf16 v[12:15], v[140:143], v[204:207], v[12:15]
	v_mfma_f32_16x16x32_bf16 v[4:7], v[156:159], v[204:207], v[4:7]
	s_waitcnt lgkmcnt(0)
	v_mfma_f32_16x16x32_bf16 v[60:63], v[152:155], v[168:171], v[60:63]
	v_mfma_f32_16x16x32_bf16 v[52:55], v[160:163], v[168:171], v[52:55]
	v_mfma_f32_16x16x32_bf16 v[44:47], v[152:155], v[192:195], v[44:47]
	v_mfma_f32_16x16x32_bf16 v[36:39], v[160:163], v[192:195], v[36:39]
	v_mfma_f32_16x16x32_bf16 v[28:31], v[152:155], v[200:203], v[28:31]
	v_mfma_f32_16x16x32_bf16 v[20:23], v[160:163], v[200:203], v[20:23]
	v_mfma_f32_16x16x32_bf16 v[12:15], v[152:155], v[208:211], v[12:15]
	v_mfma_f32_16x16x32_bf16 v[4:7], v[160:163], v[208:211], v[4:7]
	s_setprio 0
	s_barrier
; #define PG8_STAGE(bufoff, gbase, voff) do { _Pragma("unroll") for (int _i = 0; _i < 2; ++_i) \
;         __builtin_amdgcn_global_load_lds((const unsigned*)((const char*)(gbase) + (voff)[_i]), (LAS unsigned*)(lds + (bufoff) + ldsw + _i * 8192), 16, 0, 0); } while (0)
; #define PG8_LDA(dst, b, h) do { _Pragma("unroll") for (int m = 0; m < 4; ++m) _Pragma("unroll") for (int k = 0; k < 2; ++k) dst[m][k] = *(const LAS bf16x8*)(lds + PG8_SA(b, h) + aoff + m * 2048 + k * 1024); } while (0)
; #define PG8_LDB(dst, b, h) do { _Pragma("unroll") for (int n = 0; n < 2; ++n) _Pragma("unroll") for (int k = 0; k < 2; ++k) dst[n][k] = *(const LAS bf16x8*)(lds + PG8_SB(b, h) + boff + n * 2048 + k * 1024); } while (0)
; #define PG8_MMA(ai, bj, At, Bt) do { __builtin_amdgcn_s_setprio(1); _Pragma("unroll") for (int m = 0; m < 4; ++m) _Pragma("unroll") for (int n = 0; n < 2; ++n) _Pragma("unroll") for (int k = 0; k < 2; ++k) \
;         acc[ai][bj][m][n] = __builtin_amdgcn_mfma_f32_16x16x32_bf16(Bt[n][k], At[m][k], acc[ai][bj][m][n], 0, 0, 0); __builtin_amdgcn_s_setprio(0); } while (0)
; #define PG8_WAIT_V(n) asm volatile("s_waitcnt vmcnt(" #n ")" ::: "memory")
; #define PG8_WAIT_L(n) asm volatile("s_waitcnt lgkmcnt(" #n ")" ::: "memory")
; #define PG8_BAR __builtin_amdgcn_s_barrier()
; #define PG8_SCHED __builtin_amdgcn_sched_barrier(0)
; template <class Epi, class Sched>
; __device__ __forceinline__ void gemm_phase(LAS unsigned char* lds, const Gemm g, const Sched& S, const Epi& E, const Ids I) {
;     ...
;             PG8_WAIT_V(6); PG8_BAR; PG8_MMA(1, 1, At, B1); PG8_BAR;
;             PG8_LDB(B0, 1, 0); PG8_SCHED; PG8_LDA(At, 1, 0); PG8_STAGE(PG8_SA(0, 1), a2 + hstep, voffA);
;             PG8_WAIT_L(8); PG8_BAR; PG8_WAIT_L(0); PG8_MMA(0, 0, At, B0); PG8_BAR; PG8_SCHED;
;             PG8_LDB(B1, 1, 1); PG8_STAGE(PG8_SB(1, 0), b3, voffB);
;             PG8_BAR; PG8_WAIT_L(0); PG8_MMA(0, 1, At, B1); PG8_BAR;
;             PG8_LDA(At, 1, 1); PG8_STAGE(PG8_SA(1, 0), a3, voffA);
;             PG8_BAR; PG8_WAIT_L(0); PG8_MMA(1, 0, At, B0); PG8_BAR; PG8_SCHED;
	s_add_u32 s40, s20, 0x40000
	s_addc_u32 s41, s21, 0
	s_add_i32 s39, s42, s25
	v_lshl_add_u64 v[140:141], s[40:41], 0, v[144:145]
	s_mov_b32 m0, s39
	s_nop 0
	global_load_lds_dwordx4 v[140:141], off
	v_lshl_add_u64 v[140:141], s[40:41], 0, v[128:129]
	s_add_i32 m0, s39, 0x2000
	s_nop 0
	global_load_lds_dwordx4 v[140:141], off
	s_waitcnt vmcnt(6)
	s_barrier
	s_setprio 1
	v_mfma_f32_16x16x32_bf16 v[56:59], v[212:215], v[164:167], v[56:59]
	v_mfma_f32_16x16x32_bf16 v[48:51], v[220:223], v[164:167], v[48:51]
	v_mfma_f32_16x16x32_bf16 v[40:43], v[212:215], v[188:191], v[40:43]
	v_mfma_f32_16x16x32_bf16 v[32:35], v[220:223], v[188:191], v[32:35]
	v_mfma_f32_16x16x32_bf16 v[24:27], v[212:215], v[196:199], v[24:27]
	v_mfma_f32_16x16x32_bf16 v[16:19], v[220:223], v[196:199], v[16:19]
	v_mfma_f32_16x16x32_bf16 v[8:11], v[212:215], v[204:207], v[8:11]
	v_mfma_f32_16x16x32_bf16 v[0:3], v[220:223], v[204:207], v[0:3]
	v_mfma_f32_16x16x32_bf16 v[56:59], v[216:219], v[168:171], v[56:59]
	v_mfma_f32_16x16x32_bf16 v[48:51], v[224:227], v[168:171], v[48:51]
	v_mfma_f32_16x16x32_bf16 v[40:43], v[216:219], v[192:195], v[40:43]
	v_mfma_f32_16x16x32_bf16 v[32:35], v[224:227], v[192:195], v[32:35]
	v_mfma_f32_16x16x32_bf16 v[24:27], v[216:219], v[200:203], v[24:27]
	v_mfma_f32_16x16x32_bf16 v[16:19], v[224:227], v[200:203], v[16:19]
	v_mfma_f32_16x16x32_bf16 v[8:11], v[216:219], v[208:211], v[8:11]
	v_mfma_f32_16x16x32_bf16 v[0:3], v[224:227], v[208:211], v[0:3]
	s_setprio 0
	s_add_i32 s39, 0, 0x18000
	v_add_u32_e32 v147, s39, v137
	s_barrier
	ds_read_b128 v[140:143], v147
	ds_read_b128 v[156:159], v147 offset:2048
	ds_read_b128 v[164:167], v139 offset:32768
	ds_read_b128 v[188:191], v139 offset:34816
	s_add_u32 s22, s22, 0x40000
	s_addc_u32 s23, s23, 0
	s_mov_b32 m0, s29
	v_lshl_add_u64 v[180:181], s[22:23], 0, v[144:145]
	ds_read_b128 v[196:199], v139 offset:36864
	ds_read_b128 v[204:207], v139 offset:38912
	ds_read_b128 v[152:155], v147 offset:1024
	ds_read_b128 v[160:163], v147 offset:3072
	ds_read_b128 v[168:171], v139 offset:33792
	ds_read_b128 v[192:195], v139 offset:35840
	ds_read_b128 v[200:203], v139 offset:37888
	ds_read_b128 v[208:211], v139 offset:39936
	global_load_lds_dwordx4 v[180:181], off
	v_lshl_add_u64 v[180:181], s[22:23], 0, v[128:129]
	s_mov_b32 m0, s30
	s_nop 0
	global_load_lds_dwordx4 v[180:181], off
	s_waitcnt lgkmcnt(8)
	s_barrier
	s_waitcnt lgkmcnt(6)
	s_setprio 1
	s_waitcnt lgkmcnt(6)
	v_mfma_f32_16x16x32_bf16 v[124:127], v[140:143], v[164:167], v[124:127]
	v_mfma_f32_16x16x32_bf16 v[116:119], v[156:159], v[164:167], v[116:119]
	v_mfma_f32_16x16x32_bf16 v[108:111], v[140:143], v[188:191], v[108:111]
	v_mfma_f32_16x16x32_bf16 v[100:103], v[156:159], v[188:191], v[100:103]
	v_mfma_f32_16x16x32_bf16 v[92:95], v[140:143], v[196:199], v[92:95]
	v_mfma_f32_16x16x32_bf16 v[84:87], v[156:159], v[196:199], v[84:87]
	v_mfma_f32_16x16x32_bf16 v[76:79], v[140:143], v[204:207], v[76:79]
	v_mfma_f32_16x16x32_bf16 v[68:71], v[156:159], v[204:207], v[68:71]
	s_waitcnt lgkmcnt(0)
	v_mfma_f32_16x16x32_bf16 v[124:127], v[152:155], v[168:171], v[124:127]
	v_mfma_f32_16x16x32_bf16 v[116:119], v[160:163], v[168:171], v[116:119]
	v_mfma_f32_16x16x32_bf16 v[108:111], v[152:155], v[192:195], v[108:111]
	v_mfma_f32_16x16x32_bf16 v[100:103], v[160:163], v[192:195], v[100:103]
	v_mfma_f32_16x16x32_bf16 v[92:95], v[152:155], v[200:203], v[92:95]
	v_mfma_f32_16x16x32_bf16 v[84:87], v[160:163], v[200:203], v[84:87]
	v_mfma_f32_16x16x32_bf16 v[76:79], v[152:155], v[208:211], v[76:79]
	v_mfma_f32_16x16x32_bf16 v[68:71], v[160:163], v[208:211], v[68:71]
	s_setprio 0
	s_barrier
	s_add_i32 s22, 0, 0x1c000
	s_add_i32 s23, s39, s25
	v_add_u32_e32 v147, s22, v137
	v_lshl_add_u64 v[134:135], v[134:135], 0, s[64:65]
	s_mov_b32 m0, s23
	ds_read_b128 v[212:215], v147
	ds_read_b128 v[220:223], v147 offset:2048
	ds_read_b128 v[216:219], v147 offset:1024
	ds_read_b128 v[224:227], v147 offset:3072
	global_load_lds_dwordx4 v[134:135], off
	v_lshl_add_u64 v[134:135], v[172:173], 0, s[64:65]
	s_add_i32 m0, s23, 0x2000
	s_nop 0
	global_load_lds_dwordx4 v[134:135], off
	s_barrier
	s_waitcnt lgkmcnt(2)
	s_setprio 1
	s_waitcnt lgkmcnt(2)
	v_mfma_f32_16x16x32_bf16 v[120:123], v[212:215], v[164:167], v[120:123]
	v_mfma_f32_16x16x32_bf16 v[112:115], v[220:223], v[164:167], v[112:115]
	v_mfma_f32_16x16x32_bf16 v[104:107], v[212:215], v[188:191], v[104:107]
	v_mfma_f32_16x16x32_bf16 v[96:99], v[220:223], v[188:191], v[96:99]
	v_mfma_f32_16x16x32_bf16 v[88:91], v[212:215], v[196:199], v[88:91]
	v_mfma_f32_16x16x32_bf16 v[80:83], v[220:223], v[196:199], v[80:83]
	v_mfma_f32_16x16x32_bf16 v[72:75], v[212:215], v[204:207], v[72:75]
	v_mfma_f32_16x16x32_bf16 v[64:67], v[220:223], v[204:207], v[64:67]
	s_waitcnt lgkmcnt(0)
	v_mfma_f32_16x16x32_bf16 v[120:123], v[216:219], v[168:171], v[120:123]
	v_mfma_f32_16x16x32_bf16 v[112:115], v[224:227], v[168:171], v[112:115]
	v_mfma_f32_16x16x32_bf16 v[104:107], v[216:219], v[192:195], v[104:107]
	v_mfma_f32_16x16x32_bf16 v[96:99], v[224:227], v[192:195], v[96:99]
	v_mfma_f32_16x16x32_bf16 v[88:91], v[216:219], v[200:203], v[88:91]
	v_mfma_f32_16x16x32_bf16 v[80:83], v[224:227], v[200:203], v[80:83]
	v_mfma_f32_16x16x32_bf16 v[72:75], v[216:219], v[208:211], v[72:75]
	v_mfma_f32_16x16x32_bf16 v[64:67], v[224:227], v[208:211], v[64:67]
	s_setprio 0
	s_mov_b32 m0, s31
	v_lshl_add_u64 v[134:135], v[176:177], 0, s[64:65]
	s_barrier
; __device__ __forceinline__ unsigned cvt_pk_bf16(float lo, float hi) { unsigned r; asm("v_cvt_pk_bf16_f32 %0, %1, %2" : "=v"(r) : "v"(lo), "v"(hi)); return r; }
; __device__ __forceinline__ float sigmoidf(float x) { return rcpf(1.0f + __expf(-x)); }
; #define PG8_STAGE(bufoff, gbase, voff) do { _Pragma("unroll") for (int _i = 0; _i < 2; ++_i) \
;         __builtin_amdgcn_global_load_lds((const unsigned*)((const char*)(gbase) + (voff)[_i]), (LAS unsigned*)(lds + (bufoff) + ldsw + _i * 8192), 16, 0, 0); } while (0)
; #define PG8_LDA(dst, b, h) do { _Pragma("unroll") for (int m = 0; m < 4; ++m) _Pragma("unroll") for (int k = 0; k < 2; ++k) dst[m][k] = *(const LAS bf16x8*)(lds + PG8_SA(b, h) + aoff + m * 2048 + k * 1024); } while (0)
; #define PG8_MMA(ai, bj, At, Bt) do { __builtin_amdgcn_s_setprio(1); _Pragma("unroll") for (int m = 0; m < 4; ++m) _Pragma("unroll") for (int n = 0; n < 2; ++n) _Pragma("unroll") for (int k = 0; k < 2; ++k) \
;         acc[ai][bj][m][n] = __builtin_amdgcn_mfma_f32_16x16x32_bf16(Bt[n][k], At[m][k], acc[ai][bj][m][n], 0, 0, 0); __builtin_amdgcn_s_setprio(0); } while (0)
; #define PG8_WAIT_V(n) asm volatile("s_waitcnt vmcnt(" #n ")" ::: "memory")
; #define PG8_WAIT_L(n) asm volatile("s_waitcnt lgkmcnt(" #n ")" ::: "memory")
; template <class Epi, class Sched>
; __device__ __forceinline__ void gemm_phase(LAS unsigned char* lds, const Gemm g, const Sched& S, const Epi& E, const Ids I) {
;     ...
;             PG8_LDA(At, 1, 1); PG8_STAGE(PG8_SA(1, 0), a3, voffA);
;             PG8_BAR; PG8_WAIT_L(0); PG8_MMA(1, 0, At, B0); PG8_BAR; PG8_SCHED;
;             PG8_STAGE(PG8_SB(1, 1), b3 + hstep, voffB);
;             PG8_WAIT_V(6); PG8_BAR; PG8_MMA(1, 1, At, B1); PG8_BAR;
;     __device__ __forceinline__ void operator()(const f32x4 (&acc)[2][2][4][2], const pg8::Unit& u, int wr, int wc, int fr, int fq) const {
;     ...
;             for (int m = 0; m < 4; ++m) { bf16_t* rowp = act + (size_t)(row0 + ai * 128 + m * 16) * FF + col0; float o[8];
; #pragma unroll
;                 for (int n = 0; n < 2; ++n) { const f32x4 gv = acc[ai][0][m][n], uv = acc[ai][1][m][n];
; #pragma unroll
;                     for (int j = 0; j < 4; ++j) o[4 * n + j] = gv[j] * sigmoidf(gv[j]) * uv[j]; }
;                 u32x4 w; w.x = cvt_pk_bf16(o[0], o[1]); w.y = cvt_pk_bf16(o[2], o[3]); w.z = cvt_pk_bf16(o[4], o[5]); w.w = cvt_pk_bf16(o[6], o[7]); *(u32x4*)rowp = w; }
	ds_read_b128 v[164:167], v139 offset:49152
	ds_read_b128 v[188:191], v139 offset:51200
	ds_read_b128 v[196:199], v139 offset:53248
	ds_read_b128 v[204:207], v139 offset:55296
	ds_read_b128 v[168:171], v139 offset:50176
	ds_read_b128 v[192:195], v139 offset:52224
	ds_read_b128 v[200:203], v139 offset:54272
	ds_read_b128 v[208:211], v139 offset:56320
	global_load_lds_dwordx4 v[134:135], off
	v_lshl_add_u64 v[134:135], v[178:179], 0, s[64:65]
	s_mov_b32 m0, s34
	s_nop 0
	global_load_lds_dwordx4 v[134:135], off
	s_barrier
	s_waitcnt lgkmcnt(4)
	s_setprio 1
	s_waitcnt lgkmcnt(4)
	v_mfma_f32_16x16x32_bf16 v[60:63], v[140:143], v[164:167], v[60:63]
	v_mfma_f32_16x16x32_bf16 v[52:55], v[156:159], v[164:167], v[52:55]
	v_mfma_f32_16x16x32_bf16 v[44:47], v[140:143], v[188:191], v[44:47]
	v_mfma_f32_16x16x32_bf16 v[36:39], v[156:159], v[188:191], v[36:39]
	v_mfma_f32_16x16x32_bf16 v[28:31], v[140:143], v[196:199], v[28:31]
	v_mfma_f32_16x16x32_bf16 v[20:23], v[156:159], v[196:199], v[20:23]
	v_mfma_f32_16x16x32_bf16 v[12:15], v[140:143], v[204:207], v[12:15]
	v_mfma_f32_16x16x32_bf16 v[4:7], v[156:159], v[204:207], v[4:7]
	s_waitcnt lgkmcnt(0)
	v_mfma_f32_16x16x32_bf16 v[60:63], v[152:155], v[168:171], v[60:63]
	v_mfma_f32_16x16x32_bf16 v[52:55], v[160:163], v[168:171], v[52:55]
	v_mfma_f32_16x16x32_bf16 v[44:47], v[152:155], v[192:195], v[44:47]
	v_mfma_f32_16x16x32_bf16 v[36:39], v[160:163], v[192:195], v[36:39]
	v_mfma_f32_16x16x32_bf16 v[28:31], v[152:155], v[200:203], v[28:31]
	v_mfma_f32_16x16x32_bf16 v[20:23], v[160:163], v[200:203], v[20:23]
	v_mfma_f32_16x16x32_bf16 v[12:15], v[152:155], v[208:211], v[12:15]
	v_mfma_f32_16x16x32_bf16 v[4:7], v[160:163], v[208:211], v[4:7]
	s_setprio 0
	s_barrier
	s_add_u32 s20, s20, 0x40080
	s_addc_u32 s21, s21, 0
	s_add_i32 s22, s22, s25
	v_lshl_add_u64 v[134:135], s[20:21], 0, v[144:145]
	s_mov_b32 m0, s22
	s_nop 0
	global_load_lds_dwordx4 v[134:135], off
	v_lshl_add_u64 v[134:135], s[20:21], 0, v[128:129]
	s_add_i32 m0, s22, 0x2000
	s_nop 0
	global_load_lds_dwordx4 v[134:135], off
	s_waitcnt vmcnt(6)
	s_barrier
	s_setprio 1
	v_mfma_f32_16x16x32_bf16 v[56:59], v[212:215], v[164:167], v[56:59]
	v_mfma_f32_16x16x32_bf16 v[48:51], v[220:223], v[164:167], v[48:51]
	v_mfma_f32_16x16x32_bf16 v[40:43], v[212:215], v[188:191], v[40:43]
	v_mfma_f32_16x16x32_bf16 v[32:35], v[220:223], v[188:191], v[32:35]
	v_mfma_f32_16x16x32_bf16 v[24:27], v[212:215], v[196:199], v[24:27]
	v_mfma_f32_16x16x32_bf16 v[16:19], v[220:223], v[196:199], v[16:19]
	v_mfma_f32_16x16x32_bf16 v[8:11], v[212:215], v[204:207], v[8:11]
	v_mfma_f32_16x16x32_bf16 v[0:3], v[220:223], v[204:207], v[0:3]
	v_mfma_f32_16x16x32_bf16 v[56:59], v[216:219], v[168:171], v[56:59]
	v_mfma_f32_16x16x32_bf16 v[48:51], v[224:227], v[168:171], v[48:51]
	v_mfma_f32_16x16x32_bf16 v[40:43], v[216:219], v[192:195], v[40:43]
	v_mfma_f32_16x16x32_bf16 v[32:35], v[224:227], v[192:195], v[32:35]
	v_mfma_f32_16x16x32_bf16 v[24:27], v[216:219], v[200:203], v[24:27]
	v_mfma_f32_16x16x32_bf16 v[16:19], v[224:227], v[200:203], v[16:19]
	v_mfma_f32_16x16x32_bf16 v[8:11], v[216:219], v[208:211], v[8:11]
	v_mfma_f32_16x16x32_bf16 v[0:3], v[224:227], v[208:211], v[0:3]
	s_setprio 0
	s_add_i32 s38, s38, 2
	s_add_u32 s18, s18, 0x100
	s_addc_u32 s19, s19, 0
	s_add_u32 s36, s36, 0x100
	s_addc_u32 s37, s37, 0
	s_cmp_gt_u32 s38, 13
	s_barrier
	s_cbranch_scc0 .LBB0_408
	v_lshl_or_b32 v142, s1, 7, v138
	v_lshl_add_u32 v140, s16, 8, v136
	v_mov_b32_e32 v160, 0xbfb8aa3b
	v_mov_b32_e32 v161, 0xbfb8aa3b
	v_mov_b32_e32 v162, 1.0
	v_mov_b32_e32 v163, 1.0
	v_ashrrev_i32_e32 v143, 31, v142
	v_mov_b64_e32 v[134:135], s[60:61]
	v_lshlrev_b64 v[164:165], 1, v[142:143]
	s_mov_b32 s1, s6
	s_mov_b32 s16, s8
	s_mov_b64 s[20:21], s[14:15]
	v_pk_mul_f32 v[152:153], v[124:125], v[160:161]
	v_pk_mul_f32 v[154:155], v[126:127], v[160:161]
	v_pk_mul_f32 v[156:157], v[116:117], v[160:161]
	v_pk_mul_f32 v[158:159], v[118:119], v[160:161]
	v_exp_f32_e32 v152, v152
	v_exp_f32_e32 v153, v153
	v_exp_f32_e32 v154, v154
	v_exp_f32_e32 v155, v155
	v_exp_f32_e32 v156, v156
	v_exp_f32_e32 v157, v157
	v_exp_f32_e32 v158, v158
	v_exp_f32_e32 v159, v159
	v_mad_i64_i32 v[166:167], s[18:19], v140, s73, v[134:135]
	v_pk_add_f32 v[152:153], v[152:153], v[162:163]
	v_pk_add_f32 v[154:155], v[154:155], v[162:163]
	v_pk_add_f32 v[156:157], v[156:157], v[162:163]
	v_pk_add_f32 v[158:159], v[158:159], v[162:163]
	v_rcp_f32_e32 v152, v152
	v_rcp_f32_e32 v153, v153
	v_rcp_f32_e32 v154, v154
	v_rcp_f32_e32 v155, v155
	v_rcp_f32_e32 v156, v156
	v_rcp_f32_e32 v157, v157
	v_rcp_f32_e32 v158, v158
	v_rcp_f32_e32 v159, v159
	v_lshl_add_u64 v[168:169], v[166:167], 0, v[164:165]
	v_pk_mul_f32 v[124:125], v[124:125], v[152:153]
	v_pk_mul_f32 v[126:127], v[126:127], v[154:155]
	v_pk_mul_f32 v[116:117], v[116:117], v[156:157]
	v_pk_mul_f32 v[118:119], v[118:119], v[158:159]
	v_pk_mul_f32 v[124:125], v[124:125], v[120:121]
	v_pk_mul_f32 v[126:127], v[126:127], v[122:123]
	v_pk_mul_f32 v[116:117], v[116:117], v[112:113]
	v_pk_mul_f32 v[118:119], v[118:119], v[114:115]
	v_cvt_pk_bf16_f32 v120, v124, v125
	v_cvt_pk_bf16_f32 v121, v126, v127
	v_cvt_pk_bf16_f32 v122, v116, v117
	v_cvt_pk_bf16_f32 v123, v118, v119
	global_store_dwordx4 v[168:169], v[120:123], off
	v_pk_mul_f32 v[152:153], v[108:109], v[160:161]
	v_pk_mul_f32 v[154:155], v[110:111], v[160:161]
	v_pk_mul_f32 v[156:157], v[100:101], v[160:161]
	v_pk_mul_f32 v[158:159], v[102:103], v[160:161]
	v_or_b32_e32 v170, 16, v140
	v_exp_f32_e32 v152, v152
	v_exp_f32_e32 v153, v153
	v_exp_f32_e32 v154, v154
	v_exp_f32_e32 v155, v155
	v_exp_f32_e32 v156, v156
	v_exp_f32_e32 v157, v157
; __device__ __forceinline__ unsigned cvt_pk_bf16(float lo, float hi) { unsigned r; asm("v_cvt_pk_bf16_f32 %0, %1, %2" : "=v"(r) : "v"(lo), "v"(hi)); return r; }
; __device__ __forceinline__ float sigmoidf(float x) { return rcpf(1.0f + __expf(-x)); }
;     __device__ __forceinline__ void operator()(const f32x4 (&acc)[2][2][4][2], const pg8::Unit& u, int wr, int wc, int fr, int fq) const {
;     ...
;             for (int m = 0; m < 4; ++m) { bf16_t* rowp = act + (size_t)(row0 + ai * 128 + m * 16) * FF + col0; float o[8];
; #pragma unroll
;                 for (int n = 0; n < 2; ++n) { const f32x4 gv = acc[ai][0][m][n], uv = acc[ai][1][m][n];
; #pragma unroll
;                     for (int j = 0; j < 4; ++j) o[4 * n + j] = gv[j] * sigmoidf(gv[j]) * uv[j]; }
;                 u32x4 w; w.x = cvt_pk_bf16(o[0], o[1]); w.y = cvt_pk_bf16(o[2], o[3]); w.z = cvt_pk_bf16(o[4], o[5]); w.w = cvt_pk_bf16(o[6], o[7]); *(u32x4*)rowp = w; }
	v_exp_f32_e32 v158, v158
	v_exp_f32_e32 v159, v159
	v_mad_i64_i32 v[166:167], s[18:19], v170, s73, v[134:135]
	v_pk_add_f32 v[152:153], v[152:153], v[162:163]
	v_pk_add_f32 v[154:155], v[154:155], v[162:163]
	v_pk_add_f32 v[156:157], v[156:157], v[162:163]
	v_pk_add_f32 v[158:159], v[158:159], v[162:163]
	v_rcp_f32_e32 v152, v152
	v_rcp_f32_e32 v153, v153
	v_rcp_f32_e32 v154, v154
	v_rcp_f32_e32 v155, v155
	v_rcp_f32_e32 v156, v156
	v_rcp_f32_e32 v157, v157
	v_rcp_f32_e32 v158, v158
	v_rcp_f32_e32 v159, v159
	v_lshl_add_u64 v[168:169], v[166:167], 0, v[164:165]
	v_pk_mul_f32 v[108:109], v[108:109], v[152:153]
	v_pk_mul_f32 v[110:111], v[110:111], v[154:155]
	v_pk_mul_f32 v[100:101], v[100:101], v[156:157]
	v_pk_mul_f32 v[102:103], v[102:103], v[158:159]
	v_pk_mul_f32 v[108:109], v[108:109], v[104:105]
	v_pk_mul_f32 v[110:111], v[110:111], v[106:107]
	v_pk_mul_f32 v[100:101], v[100:101], v[96:97]
	v_pk_mul_f32 v[102:103], v[102:103], v[98:99]
	v_cvt_pk_bf16_f32 v104, v108, v109
	v_cvt_pk_bf16_f32 v105, v110, v111
	v_cvt_pk_bf16_f32 v106, v100, v101
	v_cvt_pk_bf16_f32 v107, v102, v103
	global_store_dwordx4 v[168:169], v[104:107], off
	v_pk_mul_f32 v[152:153], v[92:93], v[160:161]
	v_pk_mul_f32 v[154:155], v[94:95], v[160:161]
	v_pk_mul_f32 v[156:157], v[84:85], v[160:161]
	v_pk_mul_f32 v[158:159], v[86:87], v[160:161]
	v_or_b32_e32 v170, 32, v140
	v_exp_f32_e32 v152, v152
	v_exp_f32_e32 v153, v153
	v_exp_f32_e32 v154, v154
	v_exp_f32_e32 v155, v155
	v_exp_f32_e32 v156, v156
	v_exp_f32_e32 v157, v157
	v_exp_f32_e32 v158, v158
	v_exp_f32_e32 v159, v159
	v_mad_i64_i32 v[166:167], s[18:19], v170, s73, v[134:135]
	v_pk_add_f32 v[152:153], v[152:153], v[162:163]
	v_pk_add_f32 v[154:155], v[154:155], v[162:163]
	v_pk_add_f32 v[156:157], v[156:157], v[162:163]
	v_pk_add_f32 v[158:159], v[158:159], v[162:163]
	v_rcp_f32_e32 v152, v152
	v_rcp_f32_e32 v153, v153
	v_rcp_f32_e32 v154, v154
	v_rcp_f32_e32 v155, v155
	v_rcp_f32_e32 v156, v156
	v_rcp_f32_e32 v157, v157
	v_rcp_f32_e32 v158, v158
	v_rcp_f32_e32 v159, v159
	v_lshl_add_u64 v[168:169], v[166:167], 0, v[164:165]
	v_pk_mul_f32 v[92:93], v[92:93], v[152:153]
	v_pk_mul_f32 v[94:95], v[94:95], v[154:155]
	v_pk_mul_f32 v[84:85], v[84:85], v[156:157]
	v_pk_mul_f32 v[86:87], v[86:87], v[158:159]
	v_pk_mul_f32 v[92:93], v[92:93], v[88:89]
	v_pk_mul_f32 v[94:95], v[94:95], v[90:91]
	v_pk_mul_f32 v[84:85], v[84:85], v[80:81]
	v_pk_mul_f32 v[86:87], v[86:87], v[82:83]
	v_cvt_pk_bf16_f32 v88, v92, v93
	v_cvt_pk_bf16_f32 v89, v94, v95
	v_cvt_pk_bf16_f32 v90, v84, v85
	v_cvt_pk_bf16_f32 v91, v86, v87
	global_store_dwordx4 v[168:169], v[88:91], off
	v_pk_mul_f32 v[152:153], v[76:77], v[160:161]
	v_pk_mul_f32 v[154:155], v[78:79], v[160:161]
	v_pk_mul_f32 v[156:157], v[68:69], v[160:161]
	v_pk_mul_f32 v[158:159], v[70:71], v[160:161]
	v_or_b32_e32 v170, 48, v140
	v_exp_f32_e32 v152, v152
	v_exp_f32_e32 v153, v153
	v_exp_f32_e32 v154, v154
	v_exp_f32_e32 v155, v155
	v_exp_f32_e32 v156, v156
	v_exp_f32_e32 v157, v157
	v_exp_f32_e32 v158, v158
	v_exp_f32_e32 v159, v159
	v_mad_i64_i32 v[166:167], s[18:19], v170, s73, v[134:135]
	v_pk_add_f32 v[152:153], v[152:153], v[162:163]
	v_pk_add_f32 v[154:155], v[154:155], v[162:163]
	v_pk_add_f32 v[156:157], v[156:157], v[162:163]
	v_pk_add_f32 v[158:159], v[158:159], v[162:163]
	v_rcp_f32_e32 v152, v152
	v_rcp_f32_e32 v153, v153
	v_rcp_f32_e32 v154, v154
	v_rcp_f32_e32 v155, v155
	v_rcp_f32_e32 v156, v156
	v_rcp_f32_e32 v157, v157
	v_rcp_f32_e32 v158, v158
	v_rcp_f32_e32 v159, v159
	v_lshl_add_u64 v[168:169], v[166:167], 0, v[164:165]
	v_pk_mul_f32 v[76:77], v[76:77], v[152:153]
	v_pk_mul_f32 v[78:79], v[78:79], v[154:155]
	v_pk_mul_f32 v[68:69], v[68:69], v[156:157]
	v_pk_mul_f32 v[70:71], v[70:71], v[158:159]
	v_pk_mul_f32 v[76:77], v[76:77], v[72:73]
	v_pk_mul_f32 v[78:79], v[78:79], v[74:75]
	v_pk_mul_f32 v[68:69], v[68:69], v[64:65]
	v_pk_mul_f32 v[70:71], v[70:71], v[66:67]
	v_cvt_pk_bf16_f32 v72, v76, v77
	v_cvt_pk_bf16_f32 v73, v78, v79
	v_cvt_pk_bf16_f32 v74, v68, v69
	v_cvt_pk_bf16_f32 v75, v70, v71
	global_store_dwordx4 v[168:169], v[72:75], off
	v_pk_mul_f32 v[152:153], v[60:61], v[160:161]
	v_pk_mul_f32 v[154:155], v[62:63], v[160:161]
	v_pk_mul_f32 v[156:157], v[52:53], v[160:161]
	v_pk_mul_f32 v[158:159], v[54:55], v[160:161]
	v_add_u32_e32 v170, 0x80, v140
	v_exp_f32_e32 v152, v152
	v_exp_f32_e32 v153, v153
	v_exp_f32_e32 v154, v154
	v_exp_f32_e32 v155, v155
	v_exp_f32_e32 v156, v156
	v_exp_f32_e32 v157, v157
	v_exp_f32_e32 v158, v158
	v_exp_f32_e32 v159, v159
	v_mad_i64_i32 v[166:167], s[18:19], v170, s73, v[134:135]
	v_pk_add_f32 v[152:153], v[152:153], v[162:163]
	v_pk_add_f32 v[154:155], v[154:155], v[162:163]
	v_pk_add_f32 v[156:157], v[156:157], v[162:163]
	v_pk_add_f32 v[158:159], v[158:159], v[162:163]
	v_rcp_f32_e32 v152, v152
	v_rcp_f32_e32 v153, v153
	v_rcp_f32_e32 v154, v154
	v_rcp_f32_e32 v155, v155
	v_rcp_f32_e32 v156, v156
	v_rcp_f32_e32 v157, v157
	v_rcp_f32_e32 v158, v158
	v_rcp_f32_e32 v159, v159
	v_lshl_add_u64 v[168:169], v[166:167], 0, v[164:165]
	v_pk_mul_f32 v[60:61], v[60:61], v[152:153]
; __device__ __forceinline__ unsigned cvt_pk_bf16(float lo, float hi) { unsigned r; asm("v_cvt_pk_bf16_f32 %0, %1, %2" : "=v"(r) : "v"(lo), "v"(hi)); return r; }
; __device__ __forceinline__ float sigmoidf(float x) { return rcpf(1.0f + __expf(-x)); }
; #define PG8_WAIT_V(n) asm volatile("s_waitcnt vmcnt(" #n ")" ::: "memory")
; #define PG8_BAR __builtin_amdgcn_s_barrier()
; template <class Epi, class Sched>
; __device__ __forceinline__ void gemm_phase(LAS unsigned char* lds, const Gemm g, const Sched& S, const Epi& E, const Ids I) {
;     ...
;         E(acc, cur, wr, wc, fr, fq);
;         if (!has_next) break;
; #pragma unroll
;         for (int a = 0; a < 2; ++a)
; #pragma unroll
;             for (int b = 0; b < 2; ++b)
; #pragma unroll
;                 for (int m = 0; m < 4; ++m)
; #pragma unroll
;                     for (int n = 0; n < 2; ++n) acc[a][b][m][n] = (f32x4){0.f, 0.f, 0.f, 0.f};
;         cur = nxt; cA = nA; cB = nB; ++ui;
;     }
;     PG8_WAIT_V(0);
;     if (wr == 0) PG8_BAR;
;     PG8_BAR;
;     __device__ __forceinline__ void operator()(const f32x4 (&acc)[2][2][4][2], const pg8::Unit& u, int wr, int wc, int fr, int fq) const {
;     ...
;             for (int m = 0; m < 4; ++m) { bf16_t* rowp = act + (size_t)(row0 + ai * 128 + m * 16) * FF + col0; float o[8];
; #pragma unroll
;                 for (int n = 0; n < 2; ++n) { const f32x4 gv = acc[ai][0][m][n], uv = acc[ai][1][m][n];
; #pragma unroll
;                     for (int j = 0; j < 4; ++j) o[4 * n + j] = gv[j] * sigmoidf(gv[j]) * uv[j]; }
;                 u32x4 w; w.x = cvt_pk_bf16(o[0], o[1]); w.y = cvt_pk_bf16(o[2], o[3]); w.z = cvt_pk_bf16(o[4], o[5]); w.w = cvt_pk_bf16(o[6], o[7]); *(u32x4*)rowp = w; }
	v_pk_mul_f32 v[62:63], v[62:63], v[154:155]
	v_pk_mul_f32 v[52:53], v[52:53], v[156:157]
	v_pk_mul_f32 v[54:55], v[54:55], v[158:159]
	v_pk_mul_f32 v[60:61], v[60:61], v[56:57]
	v_pk_mul_f32 v[62:63], v[62:63], v[58:59]
	v_pk_mul_f32 v[52:53], v[52:53], v[48:49]
	v_pk_mul_f32 v[54:55], v[54:55], v[50:51]
	v_cvt_pk_bf16_f32 v56, v60, v61
	v_cvt_pk_bf16_f32 v57, v62, v63
	v_cvt_pk_bf16_f32 v58, v52, v53
	v_cvt_pk_bf16_f32 v59, v54, v55
	global_store_dwordx4 v[168:169], v[56:59], off
	v_pk_mul_f32 v[152:153], v[44:45], v[160:161]
	v_pk_mul_f32 v[154:155], v[46:47], v[160:161]
	v_pk_mul_f32 v[156:157], v[36:37], v[160:161]
	v_pk_mul_f32 v[158:159], v[38:39], v[160:161]
	v_add_u32_e32 v170, 0x90, v140
	v_exp_f32_e32 v152, v152
	v_exp_f32_e32 v153, v153
	v_exp_f32_e32 v154, v154
	v_exp_f32_e32 v155, v155
	v_exp_f32_e32 v156, v156
	v_exp_f32_e32 v157, v157
	v_exp_f32_e32 v158, v158
	v_exp_f32_e32 v159, v159
	v_mad_i64_i32 v[166:167], s[18:19], v170, s73, v[134:135]
	v_pk_add_f32 v[152:153], v[152:153], v[162:163]
	v_pk_add_f32 v[154:155], v[154:155], v[162:163]
	v_pk_add_f32 v[156:157], v[156:157], v[162:163]
	v_pk_add_f32 v[158:159], v[158:159], v[162:163]
	v_rcp_f32_e32 v152, v152
	v_rcp_f32_e32 v153, v153
	v_rcp_f32_e32 v154, v154
	v_rcp_f32_e32 v155, v155
	v_rcp_f32_e32 v156, v156
	v_rcp_f32_e32 v157, v157
	v_rcp_f32_e32 v158, v158
	v_rcp_f32_e32 v159, v159
	v_lshl_add_u64 v[168:169], v[166:167], 0, v[164:165]
	v_pk_mul_f32 v[44:45], v[44:45], v[152:153]
	v_pk_mul_f32 v[46:47], v[46:47], v[154:155]
	v_pk_mul_f32 v[36:37], v[36:37], v[156:157]
	v_pk_mul_f32 v[38:39], v[38:39], v[158:159]
	v_pk_mul_f32 v[44:45], v[44:45], v[40:41]
	v_pk_mul_f32 v[46:47], v[46:47], v[42:43]
	v_pk_mul_f32 v[36:37], v[36:37], v[32:33]
	v_pk_mul_f32 v[38:39], v[38:39], v[34:35]
	v_cvt_pk_bf16_f32 v40, v44, v45
	v_cvt_pk_bf16_f32 v41, v46, v47
	v_cvt_pk_bf16_f32 v42, v36, v37
	v_cvt_pk_bf16_f32 v43, v38, v39
	global_store_dwordx4 v[168:169], v[40:43], off
	v_pk_mul_f32 v[152:153], v[28:29], v[160:161]
	v_pk_mul_f32 v[154:155], v[30:31], v[160:161]
	v_pk_mul_f32 v[156:157], v[20:21], v[160:161]
	v_pk_mul_f32 v[158:159], v[22:23], v[160:161]
	v_add_u32_e32 v170, 0xa0, v140
	v_exp_f32_e32 v152, v152
	v_exp_f32_e32 v153, v153
	v_exp_f32_e32 v154, v154
	v_exp_f32_e32 v155, v155
	v_exp_f32_e32 v156, v156
	v_exp_f32_e32 v157, v157
	v_exp_f32_e32 v158, v158
	v_exp_f32_e32 v159, v159
	v_mad_i64_i32 v[166:167], s[18:19], v170, s73, v[134:135]
	v_pk_add_f32 v[152:153], v[152:153], v[162:163]
	v_pk_add_f32 v[154:155], v[154:155], v[162:163]
	v_pk_add_f32 v[156:157], v[156:157], v[162:163]
	v_pk_add_f32 v[158:159], v[158:159], v[162:163]
	v_rcp_f32_e32 v152, v152
	v_rcp_f32_e32 v153, v153
	v_rcp_f32_e32 v154, v154
	v_rcp_f32_e32 v155, v155
	v_rcp_f32_e32 v156, v156
	v_rcp_f32_e32 v157, v157
	v_rcp_f32_e32 v158, v158
	v_rcp_f32_e32 v159, v159
	v_lshl_add_u64 v[168:169], v[166:167], 0, v[164:165]
	v_pk_mul_f32 v[28:29], v[28:29], v[152:153]
	v_pk_mul_f32 v[30:31], v[30:31], v[154:155]
	v_pk_mul_f32 v[20:21], v[20:21], v[156:157]
	v_pk_mul_f32 v[22:23], v[22:23], v[158:159]
	v_pk_mul_f32 v[28:29], v[28:29], v[24:25]
	v_pk_mul_f32 v[30:31], v[30:31], v[26:27]
	v_pk_mul_f32 v[20:21], v[20:21], v[16:17]
	v_pk_mul_f32 v[22:23], v[22:23], v[18:19]
	v_cvt_pk_bf16_f32 v24, v28, v29
	v_cvt_pk_bf16_f32 v25, v30, v31
	v_cvt_pk_bf16_f32 v26, v20, v21
	v_cvt_pk_bf16_f32 v27, v22, v23
	global_store_dwordx4 v[168:169], v[24:27], off
	v_pk_mul_f32 v[152:153], v[12:13], v[160:161]
	v_pk_mul_f32 v[154:155], v[14:15], v[160:161]
	v_pk_mul_f32 v[156:157], v[4:5], v[160:161]
	v_pk_mul_f32 v[158:159], v[6:7], v[160:161]
	v_add_u32_e32 v170, 0xb0, v140
	v_exp_f32_e32 v152, v152
	v_exp_f32_e32 v153, v153
	v_exp_f32_e32 v154, v154
	v_exp_f32_e32 v155, v155
	v_exp_f32_e32 v156, v156
	v_exp_f32_e32 v157, v157
	v_exp_f32_e32 v158, v158
	v_exp_f32_e32 v159, v159
	v_mad_i64_i32 v[166:167], s[18:19], v170, s73, v[134:135]
	v_pk_add_f32 v[152:153], v[152:153], v[162:163]
	v_pk_add_f32 v[154:155], v[154:155], v[162:163]
	v_pk_add_f32 v[156:157], v[156:157], v[162:163]
	v_pk_add_f32 v[158:159], v[158:159], v[162:163]
	v_rcp_f32_e32 v152, v152
	v_rcp_f32_e32 v153, v153
	v_rcp_f32_e32 v154, v154
	v_rcp_f32_e32 v155, v155
	v_rcp_f32_e32 v156, v156
	v_rcp_f32_e32 v157, v157
	v_rcp_f32_e32 v158, v158
	v_rcp_f32_e32 v159, v159
	v_lshl_add_u64 v[168:169], v[166:167], 0, v[164:165]
	v_pk_mul_f32 v[12:13], v[12:13], v[152:153]
	v_pk_mul_f32 v[14:15], v[14:15], v[154:155]
	v_pk_mul_f32 v[4:5], v[4:5], v[156:157]
	v_pk_mul_f32 v[6:7], v[6:7], v[158:159]
	v_pk_mul_f32 v[12:13], v[12:13], v[8:9]
	v_pk_mul_f32 v[14:15], v[14:15], v[10:11]
	v_pk_mul_f32 v[4:5], v[4:5], v[0:1]
	v_pk_mul_f32 v[6:7], v[6:7], v[2:3]
	v_cvt_pk_bf16_f32 v8, v12, v13
	v_cvt_pk_bf16_f32 v9, v14, v15
	v_cvt_pk_bf16_f32 v10, v4, v5
	v_cvt_pk_bf16_f32 v11, v6, v7
	global_store_dwordx4 v[168:169], v[8:11], off
	s_nop 1
	s_mov_b64 s[18:19], s[10:11]
	s_and_b64 vcc, exec, s[4:5]
	s_cbranch_vccz .LBB0_401
	s_waitcnt vmcnt(0)
	s_cmpk_gt_u32 s24, 0xff
	v_readlane_b32 s34, v254, 46
	s_cbranch_scc1 .LBB0_412
	s_barrier

; #define LAS __attribute__((address_space(3)))
; __device__ __forceinline__ int make_tid(int wv) { int lane_v; asm volatile("v_mbcnt_lo_u32_b32 %0, -1, 0\n\tv_mbcnt_hi_u32_b32 %0, -1, %0" : "=v"(lane_v)); return wv * 64 + lane_v; }
; __device__ __forceinline__ void phase_m2(PP P, int l, LAS unsigned char* lds, const Ids I) {
;     const int tid_local = make_tid(I.wv);
;     const int tid = TID, d = tid; unsigned char* ws = P->ws;
;     const bf16_t* PR = (const bf16_t*)(ws + WS_R1); const bf16_t* arr = (const bf16_t*)(ws + WS_R2); const size_t AS = (size_t)MT * 512;
;     bf16_t* ymix = (bf16_t*)(ws + WS_HB);
;     LAS bf16_t* SGH = (LAS bf16_t*)lds; LAS bf16_t* SGL = SGH + 16 * 136;
;     LAS float* LY = (LAS float*)(SGL + 16 * 136); LAS float* LR = LY + 5632; LAS float* LK = LR + 5632; LAS float* LV = LK + 5632; LAS float* G = LV + 5632;
;     const float* mu = P->in[I_MU] + (size_t)l * PW;
;     const float lnw = P->in[I_LNW][l * 512 + d], lnb = P->in[I_LNB][l * 512 + d], rk = P->in[I_RK][l * 512 + d];
;     const int lane = tid & 63, quad = lane >> 4, l15 = lane & 15, hd = __builtin_amdgcn_readfirstlane(tid >> 6);
;     bf16x8 bfh[4][4], bfl[4][4];
; #pragma unroll
;     for (int nt = 0; nt < 4; ++nt) { const int dd = hd * 64 + nt * 16 + l15;
; #pragma unroll
;         for (int ks = 0; ks < 4; ++ks) { const float* gp = P->in[I_G2] + ((size_t)l * 128 + ks * 32 + quad * 8) * 512 + dd; unsigned h0, h1, h2, h3, l0, l1, l2, l3;
;             split_pk(gp[0], gp[512], h0, l0); split_pk(gp[1024], gp[1536], h1, l1); split_pk(gp[2048], gp[2560], h2, l2); split_pk(gp[3072], gp[3584], h3, l3);
;             bfh[nt][ks] = __builtin_bit_cast(bf16x8, (u32x4){h0, h1, h2, h3}); bfl[nt][ks] = __builtin_bit_cast(bf16x8, (u32x4){l0, l1, l2, l3}); } }
;     for (int idx = tid; idx < 5 * 136; idx += 512) { SGH[11 * 136 + idx] = (bf16_t)0; SGL[11 * 136 + idx] = (bf16_t)0; }
;     for (int u = BID; u < MT / 11; u += NB) {
;         const int r0 = u * 11;
.LBB0_430:
	s_or_b64 exec, exec, s[6:7]
	s_cmpk_gt_i32 s93, 0x5ff
	s_cbranch_scc1 .LBB0_499
	v_readlane_b32 s1, v254, 42
	s_add_u32 s4, s4, s1
	v_and_b32_e32 v154, 0x7f, v128
	s_addc_u32 s5, s5, 0
	s_lshl_b32 s0, s0, 2
	v_lshlrev_b32_e32 v144, 2, v154
	s_add_i32 s3, s0, 0
	v_lshl_add_u64 v[130:131], s[4:5], 0, v[144:145]
	s_mov_b64 s[0:1], 0x1a00
	v_lshlrev_b32_e32 v129, 3, v136
	v_lshl_add_u64 v[156:157], v[130:131], 0, s[0:1]
	v_and_b32_e32 v129, 0x1f8, v129
	v_readlane_b32 s0, v254, 35
	v_lshlrev_b32_e32 v144, 1, v129
	v_readlane_b32 s1, v254, 36
	v_lshlrev_b32_e32 v130, 2, v129
	v_add_u32_e32 v132, 0, v130
	v_lshl_add_u64 v[158:159], s[0:1], 0, v[144:145]
	v_readlane_b32 s0, v254, 37
	v_readlane_b32 s1, v254, 38
	s_add_i32 s3, s3, 0x18200
	v_lshlrev_b32_e32 v131, 1, v139
	v_lshl_add_u64 v[160:161], s[0:1], 0, v[144:145]
	v_readlane_b32 s0, v254, 39
	v_readlane_b32 s1, v254, 40
	v_lshl_add_u32 v134, v138, 2, s3
	v_ashrrev_i32_e32 v188, 7, v128
	v_lshl_add_u64 v[162:163], s[0:1], 0, v[144:145]
	v_readlane_b32 s0, v254, 6
	s_movk_i32 s3, 0x88
	v_add_u32_e32 v135, 0x200, v128
	v_add_u32_e32 v129, s0, v130
	v_mul_u32_u24_e32 v130, 0x88, v138
	v_lshlrev_b32_e32 v130, 1, v130
	s_movk_i32 s0, 0x580
	v_add3_u32 v187, 0, v130, v131
	v_cmp_gt_i32_e64 s[4:5], s0, v128
	v_mad_u64_u32 v[130:131], s[0:1], v188, s3, v[154:155]
	s_movk_i32 s0, 0x380
	v_ashrrev_i32_e32 v190, 7, v135
	v_lshl_add_u32 v189, v130, 1, 0
	v_cmp_gt_i32_e64 s[6:7], s0, v128
	v_mad_u64_u32 v[130:131], s[0:1], v190, s3, v[154:155]
	v_lshl_add_u32 v191, v130, 1, 0
	v_add_u32_e32 v130, 0x400, v128
	s_movk_i32 s0, 0x180
	v_ashrrev_i32_e32 v192, 7, v130
	v_cmp_gt_i32_e64 s[8:9], s0, v128
	v_mad_u64_u32 v[130:131], s[0:1], v192, s3, v[154:155]
	s_movk_i32 s0, 0x2c0
	s_nop 0
	v_cmp_gt_i32_e64 s[10:11], s0, v128
	v_ashrrev_i32_e32 v164, 6, v128
	s_movk_i32 s0, 0xc0
	v_ashrrev_i32_e32 v166, 6, v135
	v_lshlrev_b32_e32 v133, 2, v137
	v_lshl_add_u32 v193, v130, 1, 0
	v_lshlrev_b32_e32 v130, 11, v164
	v_cmp_gt_i32_e64 s[12:13], s0, v128
	v_lshlrev_b32_e32 v128, 11, v166
	v_add_u32_e32 v194, v132, v130
	v_add_u32_e32 v195, v129, v130
	v_add_u32_e32 v197, v129, v128
	v_or_b32_e32 v129, 1, v133
	v_or_b32_e32 v130, 2, v133
	v_or_b32_e32 v131, 3, v133
	s_lshl_b32 s0, s25, 8
	v_add_u32_e32 v196, v132, v128
	v_lshlrev_b32_e32 v128, 13, v137
	v_cmp_gt_u32_e64 s[16:17], 11, v129
	v_lshlrev_b32_e32 v129, 11, v129
	v_cmp_gt_u32_e64 s[18:19], 11, v130
	v_lshlrev_b32_e32 v130, 11, v130
	v_cmp_gt_u32_e64 s[20:21], 11, v131
	v_lshlrev_b32_e32 v131, 11, v131
	s_add_i32 s0, s0, 0
	v_ashrrev_i32_e32 v165, 31, v164
	v_ashrrev_i32_e32 v167, 31, v166
	v_cmp_ne_u32_e64 s[14:15], 3, v137
	v_lshl_add_u64 v[168:169], s[78:79], 0, v[144:145]
	v_lshl_add_u32 v198, v136, 2, s0
	v_add_u32_e32 v199, v134, v128
	v_add_u32_e32 v200, v134, v129
	v_add_u32_e32 v201, v134, v130
	v_add_u32_e32 v202, v134, v131
	s_mov_b32 s3, s93
	s_branch .LBB0_433
	s_nop 0
	s_nop 0
	s_nop 0
	s_nop 0
	s_nop 0
	s_nop 0
	s_nop 0
	s_nop 0
	s_nop 0
	s_nop 0
	s_nop 0
	s_nop 0
	s_nop 0
	s_nop 0
	s_nop 0
	s_nop 0
	s_nop 0
	s_nop 0
	s_nop 0
	s_nop 0
	s_nop 0
	s_nop 0
	s_nop 0
	s_nop 0
	s_nop 0
	s_nop 0
	s_nop 0
	s_nop 0
	s_nop 0
	s_nop 0
	s_nop 0
	s_nop 0
	s_nop 0
	s_nop 0
	s_nop 0
	s_nop 0
	s_nop 0
	s_nop 0
	s_nop 0
	s_nop 0
	s_nop 0
	s_nop 0
	s_nop 0
	s_nop 0
	s_nop 0
	s_nop 0
	s_nop 0
	s_nop 0
	s_nop 0
	s_nop 0
	s_nop 0
	s_nop 0
	s_nop 0
	s_nop 0
	s_nop 0
	s_nop 0
	s_nop 0
	s_nop 0
	s_nop 0
	s_nop 0
	s_nop 0
	s_nop 0
	s_nop 0
	s_nop 0
	s_nop 0
	s_nop 0
	s_nop 0
	s_nop 0
	s_nop 0
	s_nop 0
	s_nop 0
	s_nop 0
	s_nop 0
	s_nop 0
	s_nop 0
	s_nop 0
	s_nop 0
	s_nop 0
	s_nop 0
	s_nop 0
	s_nop 0
	s_nop 0
	s_nop 0
	s_nop 0
	s_nop 0
	s_nop 0
	s_nop 0
	s_nop 0
	s_nop 0
	s_nop 0
	s_nop 0
	s_nop 0
	s_nop 0
	s_nop 0
	s_nop 0
	s_nop 0
	s_nop 0
	s_nop 0
	s_nop 0
	s_nop 0
	s_nop 0
	s_nop 0
	s_nop 0
